# hyena: per-channel filter bias via early scalar load instead of a vector load + wait after the main loop
# speedup vs baseline: 1.0032x; 1.0032x over previous
; DEV int tidx() { return tidx_full() & 255; }
; template <int BG>
; DEV void hyena_item_mfma(const Params& p, int g, int item, char* smem, int half) {
;     ...
;   const u16* RK = (const u16*)(p.ws + OFF_KK) + (g ? (size_t)512 * 8192 : 0) + (size_t)c * 2 * L;
;   const float* cw = p.in[I_CONVW];
;   const float* cb = p.in[I_CONVB];
;   const int tid = tidx();
;   __syncthreads();
;   if (half == 0) {
; #pragma unroll 8
;     for (int e = tid; e < 2 * L / 8; e += 256) ((uint4*)smem)[e] = ((const uint4*)RK)[e];
;   } else {
; #pragma unroll 4
;     for (int e = tid; e < 2 * L / 8; e += 256) {
;       const uint4 v = ((const uint4*)RK)[e];
;       const unsigned nx = (8 * e + 8 < 2 * L) ? (unsigned)RK[8 * e + 8] : 0u;
;       uint4 o;
;       o.x = (v.x >> 16) | (v.y << 16);
;       o.y = (v.y >> 16) | (v.z << 16);
;       o.z = (v.z >> 16) | (v.w << 16);
;       o.w = (v.w >> 16) | (nx << 16);
;       ((uint4*)(smem + RK1))[e] = o;
;     }
;   }
;   {
;     const float wx1_0 = cw[0 * 1536 + 512 + c], wx1_1 = cw[1 * 1536 + 512 + c], wx1_2 = cw[2 * 1536 + 512 + c], bx1 = cb[512 + c];
;     const float wv_0 = cw[0 * 1536 + 1024 + c], wv_1 = cw[1 * 1536 + 1024 + c], wv_2 = cw[2 * 1536 + 1024 + c], bv = cb[1024 + c];
; #pragma unroll 4
;     for (int e = tid; e < BG * L / 8; e += 256) {
;       const int bl = e / (L / 8), t = (e % (L / 8)) * 8;
;       const int b = bgi * BG + bl;
;       const F8 a = conv8(UHY + ((size_t)b * 1536 + 1024 + c) * L, t, L, wv_0, wv_1, wv_2, bv);
;       const F8 x = conv8(UHY + ((size_t)b * 1536 + 512 + c) * L, t, L, wx1_0, wx1_1, wx1_2, bx1);
;     ...
;     const float fbias = p.in[I_FBIAS][c];
.LBB0_738:
	v_readlane_b32 s36, v249, 32
	v_readlane_b32 s37, v249, 33
	s_lshl_b64 s[24:25], s[18:19], 2
	v_readlane_b32 s100, v249, 20
	v_readlane_b32 s101, v249, 21
	s_nop 0
	s_add_u32 s100, s100, s24
	s_addc_u32 s101, s101, s25
	s_load_dword s32, s[100:101], 0x0
	v_readlane_b32 s38, v249, 34
	v_readlane_b32 s39, v249, 35
	s_mov_b64 s[8:9], s[36:37]
	s_add_u32 s20, s8, s24
	s_mov_b64 s[10:11], s[38:39]
	s_addc_u32 s21, s9, s25
	s_add_u32 s22, s10, s24
	s_addc_u32 s23, s11, s25
	global_load_dword v10, v208, s[20:21]
	global_load_dword v11, v209, s[20:21] offset:2048
	global_load_dword v12, v210, s[20:21]
	global_load_dword v13, v210, s[22:23]
	global_load_dword v14, v208, s[20:21] offset:2048
	global_load_dword v15, v165, s[20:21] offset:2048
	global_load_dword v16, v165, s[22:23] offset:2048
	global_load_dword v17, v211, s[20:21]
	s_lshl_b32 s0, s35, 1
	s_and_b32 s36, s0, 2
	s_add_u32 s4, s18, 0x400
	s_addc_u32 s5, s19, 0
	s_add_u32 s8, s18, 0x200
	s_waitcnt vmcnt(9)
	v_lshlrev_b32_e32 v148, 3, v146
	s_addc_u32 s9, s19, 0
	v_lshrrev_b32_e32 v18, 2, v146
	s_mov_b64 s[10:11], 0
	v_mov_b32_e32 v19, v148
	v_mov_b32_e32 v20, v145
	v_mov_b32_e32 v21, v146
	v_readlane_b32 s40, v249, 36
	v_readlane_b32 s41, v249, 37
	v_readlane_b32 s42, v249, 38
	v_readlane_b32 s43, v249, 39
	v_readlane_b32 s44, v249, 40
	v_readlane_b32 s45, v249, 41
	v_readlane_b32 s46, v249, 42
	v_readlane_b32 s47, v249, 43
	v_readlane_b32 s48, v249, 44
	v_readlane_b32 s49, v249, 45
	v_readlane_b32 s50, v249, 46
	v_readlane_b32 s51, v249, 47
	s_mov_b32 s100, 0
	v_lshrrev_b32_e32 v52, 10, v21
	v_add_u32_e32 v52, s36, v52
	v_mul_u32_u24_e32 v52, 0x600, v52
	v_mov_b32_e32 v53, 0
	v_lshl_add_u64 v[54:55], s[4:5], 0, v[52:53]
	v_lshlrev_b64 v[54:55], 14, v[54:55]
	v_lshl_add_u64 v[54:55], s[74:75], 0, v[54:55]
	v_and_b32_e32 v56, 0x1ff8, v19
	v_lshlrev_b32_e32 v58, 1, v56
	v_mov_b32_e32 v59, 0
	v_lshl_add_u64 v[54:55], v[54:55], 0, v[58:59]
	global_load_dwordx4 v[40:43], v[54:55], off
	v_cmp_ne_u32_e32 vcc, 0, v56
	s_movk_i32 s0, 0x1ff8
	v_cmp_ne_u32_e64 s[0:1], s0, v56
	v_mov_b32_e32 v48, 0
	v_mov_b32_e32 v49, 0
	v_mov_b32_e32 v50, 0
	v_mov_b32_e32 v51, 0
	s_and_saveexec_b64 s[12:13], vcc
	global_load_ushort v48, v[54:55], off offset:-2
	s_mov_b64 exec, s[12:13]
	s_and_saveexec_b64 s[12:13], s[0:1]
	global_load_ushort v49, v[54:55], off offset:16
	s_mov_b64 exec, s[12:13]
	v_lshl_add_u64 v[54:55], s[8:9], 0, v[52:53]
	v_lshlrev_b64 v[54:55], 14, v[54:55]
	v_lshl_add_u64 v[54:55], s[74:75], 0, v[54:55]
	v_lshl_add_u64 v[54:55], v[54:55], 0, v[58:59]
	global_load_dwordx4 v[44:47], v[54:55], off
	s_and_saveexec_b64 s[12:13], vcc
	global_load_ushort v50, v[54:55], off offset:-2
	s_mov_b64 exec, s[12:13]
	s_and_saveexec_b64 s[12:13], s[0:1]
	global_load_ushort v51, v[54:55], off offset:16
	s_mov_b64 exec, s[12:13]

; DEV float bflo(unsigned w) { return __uint_as_float(w << 16); }
; DEV float bfhi(unsigned w) { return __uint_as_float(w & 0xffff0000u); }
; template <int BG>
; DEV void hyena_item_mfma(const Params& p, int g, int item, char* smem, int half) {
;     ...
;   {
;     const float fbias = p.in[I_FBIAS][c];
; #pragma unroll
;     for (int nt = 0; nt < 2; ++nt)
; #pragma unroll
;       for (int mi = 0; mi < 2; ++mi)
; #pragma unroll
;         for (int rg = 0; rg < 4; ++rg) {
;           const int col = colw + 32 * nt + n, i0 = 32 * mi + 8 * rg + 4 * hh;
;           char* pv = Vl + col * VROW + i0 * 2;
;           const uint2 w = *(const uint2*)pv;
;           const float t0 = acc[nt][mi][4 * rg + 0] + bflo(w.x) * fbias;
;           const float t1 = acc[nt][mi][4 * rg + 1] + bfhi(w.x) * fbias;
;           const float t2 = acc[nt][mi][4 * rg + 2] + bflo(w.y) * fbias;
;           const float t3 = acc[nt][mi][4 * rg + 3] + bfhi(w.y) * fbias;
;           *(uint2*)pv = make_uint2(pack2(t0, t1), pack2(t2, t3));
;         }
;   }
.LBB0_754:
	s_or_b64 exec, exec, s[0:1]
	v_readlane_b32 s40, v249, 16
	v_readlane_b32 s41, v249, 17
	v_readlane_b32 s42, v249, 18
	v_readlane_b32 s43, v249, 19
	v_readlane_b32 s44, v249, 20
	v_readlane_b32 s45, v249, 21
	v_readlane_b32 s46, v249, 22
	v_readlane_b32 s47, v249, 23
	v_readlane_b32 s48, v249, 24
	v_readlane_b32 s49, v249, 25
	s_mov_b64 s[40:41], s[44:45]
	s_add_u32 s0, s40, s24
	s_addc_u32 s1, s41, s25
	s_waitcnt lgkmcnt(0)
	s_barrier
	v_mov_b32_e32 v64, s32
	v_mul_u32_u24_e32 v65, 0x90, v150
	v_add3_u32 v65, s27, v65, v149
	ds_read2_b64 v[66:69], v65 offset1:2
	ds_read2_b64 v[70:73], v65 offset0:4 offset1:6
	v_lshlrev_b32_e32 v164, 1, v148
	s_mov_b32 s10, 0
	v_cmp_ne_u32_e64 s[0:1], 0, v146
	s_waitcnt lgkmcnt(1)
	v_lshlrev_b32_e32 v74, 16, v66
	v_and_b32_e32 v66, 0xffff0000, v66
	s_mov_b64 s[4:5], 0
	v_readlane_b32 s50, v249, 26
	v_readlane_b32 s51, v249, 27
	v_readlane_b32 s52, v249, 28
	v_readlane_b32 s53, v249, 29
	v_readlane_b32 s54, v249, 30
	v_readlane_b32 s55, v249, 31
	s_mov_b64 s[42:43], s[46:47]
	s_mov_b64 s[44:45], s[48:49]
	s_waitcnt vmcnt(0)
	v_fmac_f32_e32 v49, v64, v66
	v_lshlrev_b32_e32 v66, 16, v67
	v_fmac_f32_e32 v48, v64, v74
	v_fmac_f32_e32 v50, v64, v66
	v_and_b32_e32 v66, 0xffff0000, v67
	v_fmac_f32_e32 v51, v64, v66
	s_nop 0
	v_cvt_pk_bf16_f32 v48, v48, v49
	s_nop 0
	v_cvt_pk_bf16_f32 v49, v50, v51
	v_lshlrev_b32_e32 v50, 16, v68
	v_fmac_f32_e32 v52, v64, v50
	v_and_b32_e32 v50, 0xffff0000, v68
	v_fmac_f32_e32 v53, v64, v50
	v_lshlrev_b32_e32 v50, 16, v69
	v_fmac_f32_e32 v54, v64, v50
	v_and_b32_e32 v50, 0xffff0000, v69
	v_fmac_f32_e32 v55, v64, v50
	s_nop 0
	v_cvt_pk_bf16_f32 v50, v52, v53
	s_nop 0
	v_cvt_pk_bf16_f32 v51, v54, v55
	ds_write2_b64 v65, v[48:49], v[50:51] offset1:2
	s_waitcnt lgkmcnt(1)
	v_lshlrev_b32_e32 v48, 16, v70
	v_lshlrev_b32_e32 v50, 16, v72
	v_fmac_f32_e32 v56, v64, v48
	v_and_b32_e32 v48, 0xffff0000, v70
	v_fmac_f32_e32 v60, v64, v50
	v_and_b32_e32 v50, 0xffff0000, v72
	v_fmac_f32_e32 v57, v64, v48
	v_lshlrev_b32_e32 v48, 16, v71
	v_fmac_f32_e32 v61, v64, v50
	v_lshlrev_b32_e32 v50, 16, v73
	v_fmac_f32_e32 v58, v64, v48
	v_and_b32_e32 v48, 0xffff0000, v71
	v_fmac_f32_e32 v62, v64, v50
	v_and_b32_e32 v50, 0xffff0000, v73
	v_fmac_f32_e32 v59, v64, v48
	s_nop 0
	v_cvt_pk_bf16_f32 v48, v56, v57
	s_nop 0
	v_cvt_pk_bf16_f32 v49, v58, v59
	v_fmac_f32_e32 v63, v64, v50
	s_nop 0
	v_cvt_pk_bf16_f32 v50, v60, v61
	s_nop 0
	v_cvt_pk_bf16_f32 v51, v62, v63
	ds_write2_b64 v65, v[48:49], v[50:51] offset0:4 offset1:6
	ds_read2_b64 v[48:51], v65 offset0:8 offset1:10
	s_waitcnt lgkmcnt(0)
	v_lshlrev_b32_e32 v52, 16, v48
	v_and_b32_e32 v48, 0xffff0000, v48
	v_fmac_f32_e32 v33, v64, v48
	v_lshlrev_b32_e32 v48, 16, v49
	v_fmac_f32_e32 v32, v64, v52
	v_fmac_f32_e32 v34, v64, v48
	v_and_b32_e32 v48, 0xffff0000, v49
	v_fmac_f32_e32 v35, v64, v48
	s_nop 0
	v_cvt_pk_bf16_f32 v32, v32, v33
	s_nop 0
	v_cvt_pk_bf16_f32 v33, v34, v35
	v_lshlrev_b32_e32 v34, 16, v50
	v_fmac_f32_e32 v36, v64, v34
	v_and_b32_e32 v34, 0xffff0000, v50
	v_fmac_f32_e32 v37, v64, v34
	v_lshlrev_b32_e32 v34, 16, v51
	v_fmac_f32_e32 v38, v64, v34
	v_and_b32_e32 v34, 0xffff0000, v51
	v_fmac_f32_e32 v39, v64, v34
	s_nop 0
	v_cvt_pk_bf16_f32 v34, v36, v37
	s_nop 0
	v_cvt_pk_bf16_f32 v35, v38, v39
	ds_write2_b64 v65, v[32:33], v[34:35] offset0:8 offset1:10
	ds_read2_b64 v[32:35], v65 offset0:12 offset1:14
	s_waitcnt lgkmcnt(0)
	v_lshlrev_b32_e32 v36, 16, v32
	v_fmac_f32_e32 v40, v64, v36
	v_and_b32_e32 v32, 0xffff0000, v32
	v_lshlrev_b32_e32 v36, 16, v34
	v_and_b32_e32 v34, 0xffff0000, v34
	v_fmac_f32_e32 v41, v64, v32
	v_lshlrev_b32_e32 v32, 16, v33
	v_fmac_f32_e32 v45, v64, v34
	v_lshlrev_b32_e32 v34, 16, v35
	v_fmac_f32_e32 v42, v64, v32
	v_and_b32_e32 v32, 0xffff0000, v33
	v_fmac_f32_e32 v46, v64, v34
	v_and_b32_e32 v34, 0xffff0000, v35
	v_fmac_f32_e32 v43, v64, v32
	s_nop 0
	v_cvt_pk_bf16_f32 v32, v40, v41
	s_nop 0
	v_cvt_pk_bf16_f32 v33, v42, v43
	v_fmac_f32_e32 v44, v64, v36
	v_fmac_f32_e32 v47, v64, v34
	s_nop 0
	v_cvt_pk_bf16_f32 v34, v44, v45
	s_nop 0
	v_cvt_pk_bf16_f32 v35, v46, v47
	v_add_u32_e32 v36, 0x1000, v65
	ds_write2_b64 v65, v[32:33], v[34:35] offset0:12 offset1:14
	ds_read2_b64 v[32:35], v36 offset0:64 offset1:66
	v_or_b32_e32 v43, 0x1800, v148
	v_mov_b32_e32 v45, s36
	s_waitcnt lgkmcnt(0)
; DEV float bflo(unsigned w) { return __uint_as_float(w << 16); }
; DEV float bfhi(unsigned w) { return __uint_as_float(w & 0xffff0000u); }
; template <int BG>
; DEV void hyena_item_mfma(const Params& p, int g, int item, char* smem, int half) {
;     ...
;   {
;     const float fbias = p.in[I_FBIAS][c];
; #pragma unroll
;     for (int nt = 0; nt < 2; ++nt)
; #pragma unroll
;       for (int mi = 0; mi < 2; ++mi)
; #pragma unroll
;         for (int rg = 0; rg < 4; ++rg) {
;           const int col = colw + 32 * nt + n, i0 = 32 * mi + 8 * rg + 4 * hh;
;           char* pv = Vl + col * VROW + i0 * 2;
;           const uint2 w = *(const uint2*)pv;
;           const float t0 = acc[nt][mi][4 * rg + 0] + bflo(w.x) * fbias;
;           const float t1 = acc[nt][mi][4 * rg + 1] + bfhi(w.x) * fbias;
;           const float t2 = acc[nt][mi][4 * rg + 2] + bflo(w.y) * fbias;
;           const float t3 = acc[nt][mi][4 * rg + 3] + bfhi(w.y) * fbias;
;           *(uint2*)pv = make_uint2(pack2(t0, t1), pack2(t2, t3));
;         }
;   }
;   __syncthreads();
;   {
;     const float wx0_0 = cw[0 * 1536 + c], wx0_1 = cw[1 * 1536 + c], wx0_2 = cw[2 * 1536 + c], bx0 = cb[c];
;     for (int e0 = tid; e0 < BG * L / 8; e0 += 256 * 4) {
	v_lshlrev_b32_e32 v37, 16, v32
	v_and_b32_e32 v32, 0xffff0000, v32
	v_fmac_f32_e32 v17, v64, v32
	v_lshlrev_b32_e32 v32, 16, v33
	v_fmac_f32_e32 v16, v64, v37
	v_fmac_f32_e32 v18, v64, v32
	v_and_b32_e32 v32, 0xffff0000, v33
	v_fmac_f32_e32 v19, v64, v32
	s_nop 0
	v_cvt_pk_bf16_f32 v16, v16, v17
	s_nop 0
	v_cvt_pk_bf16_f32 v17, v18, v19
	v_lshlrev_b32_e32 v18, 16, v34
	v_fmac_f32_e32 v20, v64, v18
	v_and_b32_e32 v18, 0xffff0000, v34
	v_fmac_f32_e32 v21, v64, v18
	v_lshlrev_b32_e32 v18, 16, v35
	v_fmac_f32_e32 v22, v64, v18
	v_and_b32_e32 v18, 0xffff0000, v35
	v_fmac_f32_e32 v23, v64, v18
	s_nop 0
	v_cvt_pk_bf16_f32 v18, v20, v21
	s_nop 0
	v_cvt_pk_bf16_f32 v19, v22, v23
	ds_write2_b64 v36, v[16:17], v[18:19] offset0:64 offset1:66
	ds_read2_b64 v[16:19], v36 offset0:68 offset1:70
	s_waitcnt lgkmcnt(0)
	v_lshlrev_b32_e32 v20, 16, v16
	v_fmac_f32_e32 v24, v64, v20
	v_and_b32_e32 v16, 0xffff0000, v16
	v_lshlrev_b32_e32 v20, 16, v18
	v_and_b32_e32 v18, 0xffff0000, v18
	v_fmac_f32_e32 v25, v64, v16
	v_lshlrev_b32_e32 v16, 16, v17
	v_fmac_f32_e32 v29, v64, v18
	v_lshlrev_b32_e32 v18, 16, v19
	v_fmac_f32_e32 v26, v64, v16
	v_and_b32_e32 v16, 0xffff0000, v17
	v_fmac_f32_e32 v30, v64, v18
	v_and_b32_e32 v18, 0xffff0000, v19
	v_fmac_f32_e32 v27, v64, v16
	s_nop 0
	v_cvt_pk_bf16_f32 v16, v24, v25
	s_nop 0
	v_cvt_pk_bf16_f32 v17, v26, v27
	v_fmac_f32_e32 v28, v64, v20
	v_fmac_f32_e32 v31, v64, v18
	s_nop 0
	v_cvt_pk_bf16_f32 v18, v28, v29
	s_nop 0
	v_cvt_pk_bf16_f32 v19, v30, v31
	ds_write2_b64 v36, v[16:17], v[18:19] offset0:68 offset1:70
	ds_read2_b64 v[16:19], v36 offset0:72 offset1:74
	v_lshl_add_u64 v[28:29], s[74:75], 0, v[164:165]
	s_waitcnt lgkmcnt(0)
	v_lshlrev_b32_e32 v20, 16, v16
	v_and_b32_e32 v16, 0xffff0000, v16
	v_fmac_f32_e32 v1, v64, v16
	v_lshlrev_b32_e32 v16, 16, v17
	v_fmac_f32_e32 v0, v64, v20
	v_fmac_f32_e32 v2, v64, v16
	v_and_b32_e32 v16, 0xffff0000, v17
	v_fmac_f32_e32 v3, v64, v16
	s_nop 0
	v_cvt_pk_bf16_f32 v0, v0, v1
	s_nop 0
	v_cvt_pk_bf16_f32 v1, v2, v3
	v_lshlrev_b32_e32 v2, 16, v18
	v_fmac_f32_e32 v4, v64, v2
	v_and_b32_e32 v2, 0xffff0000, v18
	v_fmac_f32_e32 v5, v64, v2
	v_lshlrev_b32_e32 v2, 16, v19
	v_fmac_f32_e32 v6, v64, v2
	v_and_b32_e32 v2, 0xffff0000, v19
	v_fmac_f32_e32 v7, v64, v2
	s_nop 0
	v_cvt_pk_bf16_f32 v2, v4, v5
	s_nop 0
	v_cvt_pk_bf16_f32 v3, v6, v7
	ds_write2_b64 v36, v[0:1], v[2:3] offset0:72 offset1:74
	ds_read2_b64 v[0:3], v36 offset0:76 offset1:78
	s_waitcnt lgkmcnt(0)
	v_lshlrev_b32_e32 v4, 16, v0
	v_fmac_f32_e32 v8, v64, v4
	v_and_b32_e32 v0, 0xffff0000, v0
	v_lshlrev_b32_e32 v4, 16, v2
	v_and_b32_e32 v2, 0xffff0000, v2
	v_fmac_f32_e32 v9, v64, v0
	v_lshlrev_b32_e32 v0, 16, v1
	v_fmac_f32_e32 v13, v64, v2
	v_lshlrev_b32_e32 v2, 16, v3
	v_fmac_f32_e32 v10, v64, v0
	v_and_b32_e32 v0, 0xffff0000, v1
	v_fmac_f32_e32 v14, v64, v2
	v_and_b32_e32 v2, 0xffff0000, v3
	v_fmac_f32_e32 v11, v64, v0
	s_nop 0
	v_cvt_pk_bf16_f32 v0, v8, v9
	s_nop 0
	v_cvt_pk_bf16_f32 v1, v10, v11
	v_fmac_f32_e32 v12, v64, v4
	v_fmac_f32_e32 v15, v64, v2
	s_nop 0
	v_cvt_pk_bf16_f32 v2, v12, v13
	s_nop 0
	v_cvt_pk_bf16_f32 v3, v14, v15
	ds_write2_b64 v36, v[0:1], v[2:3] offset0:76 offset1:78
	s_waitcnt lgkmcnt(0)
	s_barrier
	global_load_dword v38, v165, s[20:21]
	global_load_dword v39, v210, s[20:21] offset:2048
	global_load_dword v40, v209, s[20:21]
	global_load_dword v41, v165, s[22:23]
	v_lshlrev_b32_e32 v0, 4, v147
	v_and_b32_e32 v0, 0x70, v0
	v_add_u32_e32 v42, s27, v0
	v_or_b32_e32 v0, 0x300, v146
	v_lshrrev_b32_e32 v0, 2, v0
	v_and_b32_e32 v44, 0xfe, v0
	v_or_b32_e32 v0, 0x200, v146
	v_lshrrev_b32_e32 v0, 2, v0
	v_and_b32_e32 v46, 0xbe, v0
	v_or_b32_e32 v0, 0x100, v146
	v_lshrrev_b32_e32 v0, 2, v0
	v_and_b32_e32 v47, 0x7e, v0
	v_lshrrev_b32_e32 v0, 2, v146
	v_and_b32_e32 v48, 62, v0
	s_branch .LBB0_756

; DEV int tidx() { return tidx_full() & 255; }
; template <int BG>
; DEV void hyena_item_mfma(const Params& p, int g, int item, char* smem, int half) {
;     ...
;   const u16* RK = (const u16*)(p.ws + OFF_KK) + (g ? (size_t)512 * 8192 : 0) + (size_t)c * 2 * L;
;   const float* cw = p.in[I_CONVW];
;   const float* cb = p.in[I_CONVB];
;   const int tid = tidx();
;   __syncthreads();
;   if (half == 0) {
; #pragma unroll 8
;     for (int e = tid; e < 2 * L / 8; e += 256) ((uint4*)smem)[e] = ((const uint4*)RK)[e];
;   } else {
; #pragma unroll 4
;     for (int e = tid; e < 2 * L / 8; e += 256) {
;       const uint4 v = ((const uint4*)RK)[e];
;       const unsigned nx = (8 * e + 8 < 2 * L) ? (unsigned)RK[8 * e + 8] : 0u;
;       uint4 o;
;       o.x = (v.x >> 16) | (v.y << 16);
;       o.y = (v.y >> 16) | (v.z << 16);
;       o.z = (v.z >> 16) | (v.w << 16);
;       o.w = (v.w >> 16) | (nx << 16);
;       ((uint4*)(smem + RK1))[e] = o;
;     }
;   }
;   {
;     const float wx1_0 = cw[0 * 1536 + 512 + c], wx1_1 = cw[1 * 1536 + 512 + c], wx1_2 = cw[2 * 1536 + 512 + c], bx1 = cb[512 + c];
;     const float wv_0 = cw[0 * 1536 + 1024 + c], wv_1 = cw[1 * 1536 + 1024 + c], wv_2 = cw[2 * 1536 + 1024 + c], bv = cb[1024 + c];
; #pragma unroll 4
;     for (int e = tid; e < BG * L / 8; e += 256) {
;       const int bl = e / (L / 8), t = (e % (L / 8)) * 8;
;       const int b = bgi * BG + bl;
;       const F8 a = conv8(UHY + ((size_t)b * 1536 + 1024 + c) * L, t, L, wv_0, wv_1, wv_2, bv);
;       const F8 x = conv8(UHY + ((size_t)b * 1536 + 512 + c) * L, t, L, wx1_0, wx1_1, wx1_2, bx1);
;     ...
;     const float fbias = p.in[I_FBIAS][c];
.LBB0_778:
	v_readlane_b32 s36, v249, 32
	v_readlane_b32 s37, v249, 33
	s_lshl_b64 s[24:25], s[18:19], 2
	v_readlane_b32 s100, v249, 20
	v_readlane_b32 s101, v249, 21
	s_nop 0
	s_add_u32 s100, s100, s24
	s_addc_u32 s101, s101, s25
	s_load_dword s32, s[100:101], 0x0
	v_readlane_b32 s38, v249, 34
	v_readlane_b32 s39, v249, 35
	s_mov_b64 s[8:9], s[36:37]
	s_add_u32 s20, s8, s24
	s_mov_b64 s[10:11], s[38:39]
	s_addc_u32 s21, s9, s25
	s_add_u32 s22, s10, s24
	s_addc_u32 s23, s11, s25
	global_load_dword v10, v208, s[20:21]
	global_load_dword v11, v209, s[20:21] offset:2048
	global_load_dword v12, v210, s[20:21]
	global_load_dword v13, v210, s[22:23]
	global_load_dword v14, v208, s[20:21] offset:2048
	global_load_dword v15, v165, s[20:21] offset:2048
	global_load_dword v16, v165, s[22:23] offset:2048
	global_load_dword v17, v211, s[20:21]
	s_lshl_b32 s0, s35, 2
	s_and_b32 s35, s0, 4
	s_add_u32 s4, s18, 0x400
	s_addc_u32 s5, s19, 0
	s_add_u32 s8, s18, 0x200
	s_addc_u32 s9, s19, 0
	v_lshrrev_b32_e32 v18, 1, v148
	s_mov_b64 s[10:11], 0
	v_mov_b32_e32 v19, v146
	v_mov_b32_e32 v20, v144
	v_mov_b32_e32 v21, v148
	v_readlane_b32 s40, v249, 36
	v_readlane_b32 s41, v249, 37
	v_readlane_b32 s42, v249, 38
	v_readlane_b32 s43, v249, 39
	v_readlane_b32 s44, v249, 40
	v_readlane_b32 s45, v249, 41
	v_readlane_b32 s46, v249, 42
	v_readlane_b32 s47, v249, 43
	v_readlane_b32 s48, v249, 44
	v_readlane_b32 s49, v249, 45
	v_readlane_b32 s50, v249, 46
	v_readlane_b32 s51, v249, 47
	s_mov_b32 s100, 0
	v_lshrrev_b32_e32 v52, 9, v21
	v_add_u32_e32 v52, s35, v52
	v_mul_u32_u24_e32 v52, 0x600, v52
	v_mov_b32_e32 v53, 0
	v_lshl_add_u64 v[54:55], s[4:5], 0, v[52:53]
	v_lshlrev_b64 v[54:55], 13, v[54:55]
	v_lshl_add_u64 v[54:55], s[74:75], 0, v[54:55]
	v_and_b32_e32 v56, 0xff8, v19
	v_lshlrev_b32_e32 v58, 1, v56
	v_mov_b32_e32 v59, 0
	v_lshl_add_u64 v[54:55], v[54:55], 0, v[58:59]
	global_load_dwordx4 v[40:43], v[54:55], off
	v_cmp_ne_u32_e32 vcc, 0, v56
	s_movk_i32 s0, 0xff8
	v_cmp_ne_u32_e64 s[0:1], s0, v56
	v_mov_b32_e32 v48, 0
	v_mov_b32_e32 v49, 0
	v_mov_b32_e32 v50, 0
	v_mov_b32_e32 v51, 0
	s_and_saveexec_b64 s[12:13], vcc
	global_load_ushort v48, v[54:55], off offset:-2
	s_mov_b64 exec, s[12:13]
	s_and_saveexec_b64 s[12:13], s[0:1]
	global_load_ushort v49, v[54:55], off offset:16
	s_mov_b64 exec, s[12:13]
	v_lshl_add_u64 v[54:55], s[8:9], 0, v[52:53]
	v_lshlrev_b64 v[54:55], 13, v[54:55]
	v_lshl_add_u64 v[54:55], s[74:75], 0, v[54:55]
	v_lshl_add_u64 v[54:55], v[54:55], 0, v[58:59]
	global_load_dwordx4 v[44:47], v[54:55], off
	s_and_saveexec_b64 s[12:13], vcc
	global_load_ushort v50, v[54:55], off offset:-2
	s_mov_b64 exec, s[12:13]
	s_and_saveexec_b64 s[12:13], s[0:1]
	global_load_ushort v51, v[54:55], off offset:16
	s_mov_b64 exec, s[12:13]

; DEV float bflo(unsigned w) { return __uint_as_float(w << 16); }
; DEV float bfhi(unsigned w) { return __uint_as_float(w & 0xffff0000u); }
; template <int BG>
; DEV void hyena_item_mfma(const Params& p, int g, int item, char* smem, int half) {
;     ...
;   {
;     const float fbias = p.in[I_FBIAS][c];
; #pragma unroll
;     for (int nt = 0; nt < 2; ++nt)
; #pragma unroll
;       for (int mi = 0; mi < 2; ++mi)
; #pragma unroll
;         for (int rg = 0; rg < 4; ++rg) {
;           const int col = colw + 32 * nt + n, i0 = 32 * mi + 8 * rg + 4 * hh;
;           char* pv = Vl + col * VROW + i0 * 2;
;           const uint2 w = *(const uint2*)pv;
;           const float t0 = acc[nt][mi][4 * rg + 0] + bflo(w.x) * fbias;
;           const float t1 = acc[nt][mi][4 * rg + 1] + bfhi(w.x) * fbias;
;           const float t2 = acc[nt][mi][4 * rg + 2] + bflo(w.y) * fbias;
;           const float t3 = acc[nt][mi][4 * rg + 3] + bfhi(w.y) * fbias;
;           *(uint2*)pv = make_uint2(pack2(t0, t1), pack2(t2, t3));
;         }
;   }
.LBB0_794:
	s_or_b64 exec, exec, s[0:1]
	v_readlane_b32 s36, v249, 16
	v_readlane_b32 s40, v249, 20
	v_readlane_b32 s41, v249, 21
	s_add_u32 s0, s40, s24
	s_addc_u32 s1, s41, s25
	s_waitcnt lgkmcnt(0)
	s_barrier
	v_mov_b32_e32 v64, s32
	v_mul_u32_u24_e32 v65, 0x90, v149
	v_add3_u32 v65, s15, v65, v145
	v_add_u32_e32 v66, 0x8000, v65
	ds_read2_b64 v[68:71], v66 offset0:16 offset1:18
	ds_read2_b64 v[72:75], v66 offset0:20 offset1:22
	s_mov_b64 s[4:5], 0x1000
	v_readlane_b32 s37, v249, 17
	s_mov_b32 s10, 0
	s_waitcnt lgkmcnt(1)
	v_lshlrev_b32_e32 v67, 16, v68
	v_cmp_ne_u32_e64 s[0:1], 0, v148
	v_readlane_b32 s38, v249, 18
	v_readlane_b32 s39, v249, 19
	v_readlane_b32 s42, v249, 22
	v_readlane_b32 s43, v249, 23
	v_readlane_b32 s44, v249, 24
	v_readlane_b32 s45, v249, 25
	v_readlane_b32 s46, v249, 26
	v_readlane_b32 s47, v249, 27
	v_readlane_b32 s48, v249, 28
	v_readlane_b32 s49, v249, 29
	v_readlane_b32 s50, v249, 30
	v_readlane_b32 s51, v249, 31
	s_waitcnt vmcnt(0)
	v_fmac_f32_e32 v48, v64, v67
	v_and_b32_e32 v67, 0xffff0000, v68
	v_fmac_f32_e32 v49, v64, v67
	v_lshlrev_b32_e32 v67, 16, v69
	v_fmac_f32_e32 v50, v64, v67
	v_and_b32_e32 v67, 0xffff0000, v69
	v_fmac_f32_e32 v51, v64, v67
	s_nop 0
	v_cvt_pk_bf16_f32 v48, v48, v49
	s_nop 0
	v_cvt_pk_bf16_f32 v49, v50, v51
	v_lshlrev_b32_e32 v50, 16, v70
	v_fmac_f32_e32 v52, v64, v50
	v_and_b32_e32 v50, 0xffff0000, v70
	v_fmac_f32_e32 v53, v64, v50
	v_lshlrev_b32_e32 v50, 16, v71
	v_fmac_f32_e32 v54, v64, v50
	v_and_b32_e32 v50, 0xffff0000, v71
	v_fmac_f32_e32 v55, v64, v50
	s_nop 0
	v_cvt_pk_bf16_f32 v50, v52, v53
	s_nop 0
	v_cvt_pk_bf16_f32 v51, v54, v55
	ds_write2_b64 v66, v[48:49], v[50:51] offset0:16 offset1:18
	s_waitcnt lgkmcnt(1)
	v_lshlrev_b32_e32 v48, 16, v72
	v_lshlrev_b32_e32 v50, 16, v74
	v_fmac_f32_e32 v56, v64, v48
	v_and_b32_e32 v48, 0xffff0000, v72
	v_fmac_f32_e32 v60, v64, v50
	v_and_b32_e32 v50, 0xffff0000, v74
	v_fmac_f32_e32 v57, v64, v48
	v_lshlrev_b32_e32 v48, 16, v73
	v_fmac_f32_e32 v61, v64, v50
	v_lshlrev_b32_e32 v50, 16, v75
	v_fmac_f32_e32 v58, v64, v48
	v_and_b32_e32 v48, 0xffff0000, v73
	v_fmac_f32_e32 v62, v64, v50
	v_and_b32_e32 v50, 0xffff0000, v75
	v_fmac_f32_e32 v59, v64, v48
	s_nop 0
	v_cvt_pk_bf16_f32 v48, v56, v57
	s_nop 0
	v_cvt_pk_bf16_f32 v49, v58, v59
	v_fmac_f32_e32 v63, v64, v50
	s_nop 0
	v_cvt_pk_bf16_f32 v50, v60, v61
	s_nop 0
	v_cvt_pk_bf16_f32 v51, v62, v63
	ds_write2_b64 v66, v[48:49], v[50:51] offset0:20 offset1:22
	ds_read2_b64 v[48:51], v66 offset0:24 offset1:26
	s_waitcnt lgkmcnt(0)
	v_lshlrev_b32_e32 v52, 16, v48
	v_and_b32_e32 v48, 0xffff0000, v48
	v_fmac_f32_e32 v33, v64, v48
	v_lshlrev_b32_e32 v48, 16, v49
	v_fmac_f32_e32 v32, v64, v52
	v_fmac_f32_e32 v34, v64, v48
	v_and_b32_e32 v48, 0xffff0000, v49
	v_fmac_f32_e32 v35, v64, v48
	s_nop 0
	v_cvt_pk_bf16_f32 v32, v32, v33
	s_nop 0
	v_cvt_pk_bf16_f32 v33, v34, v35
	v_lshlrev_b32_e32 v34, 16, v50
	v_fmac_f32_e32 v36, v64, v34
	v_and_b32_e32 v34, 0xffff0000, v50
	v_fmac_f32_e32 v37, v64, v34
	v_lshlrev_b32_e32 v34, 16, v51
	v_fmac_f32_e32 v38, v64, v34
	v_and_b32_e32 v34, 0xffff0000, v51
	v_fmac_f32_e32 v39, v64, v34
	s_nop 0
	v_cvt_pk_bf16_f32 v34, v36, v37
	s_nop 0
	v_cvt_pk_bf16_f32 v35, v38, v39
	ds_write2_b64 v66, v[32:33], v[34:35] offset0:24 offset1:26
	ds_read2_b64 v[32:35], v66 offset0:28 offset1:30
	v_add_u32_e32 v49, 0x800, v146
	v_mov_b32_e32 v50, s35
	s_waitcnt lgkmcnt(0)
	v_lshlrev_b32_e32 v36, 16, v32
	v_fmac_f32_e32 v40, v64, v36
	v_and_b32_e32 v32, 0xffff0000, v32
	v_lshlrev_b32_e32 v36, 16, v34
	v_and_b32_e32 v34, 0xffff0000, v34
	v_fmac_f32_e32 v41, v64, v32
	v_lshlrev_b32_e32 v32, 16, v33
	v_fmac_f32_e32 v45, v64, v34
	v_lshlrev_b32_e32 v34, 16, v35
	v_fmac_f32_e32 v42, v64, v32
	v_and_b32_e32 v32, 0xffff0000, v33
	v_fmac_f32_e32 v46, v64, v34
	v_and_b32_e32 v34, 0xffff0000, v35
	v_fmac_f32_e32 v43, v64, v32
	s_nop 0
	v_cvt_pk_bf16_f32 v32, v40, v41
	s_nop 0
	v_cvt_pk_bf16_f32 v33, v42, v43
	v_fmac_f32_e32 v44, v64, v36
	v_fmac_f32_e32 v47, v64, v34
	s_nop 0
	v_cvt_pk_bf16_f32 v34, v44, v45
	s_nop 0
	v_cvt_pk_bf16_f32 v35, v46, v47
	v_add_u32_e32 v36, 0x9000, v65
	ds_write2_b64 v66, v[32:33], v[34:35] offset0:28 offset1:30
	ds_read2_b64 v[32:35], v36 offset0:80 offset1:82
	v_or_b32_e32 v43, 0xfffffc00, v148
	s_waitcnt lgkmcnt(0)
; DEV float bflo(unsigned w) { return __uint_as_float(w << 16); }
; DEV float bfhi(unsigned w) { return __uint_as_float(w & 0xffff0000u); }
; template <int BG>
; DEV void hyena_item_mfma(const Params& p, int g, int item, char* smem, int half) {
;     ...
;   {
;     const float fbias = p.in[I_FBIAS][c];
; #pragma unroll
;     for (int nt = 0; nt < 2; ++nt)
; #pragma unroll
;       for (int mi = 0; mi < 2; ++mi)
; #pragma unroll
;         for (int rg = 0; rg < 4; ++rg) {
;           const int col = colw + 32 * nt + n, i0 = 32 * mi + 8 * rg + 4 * hh;
;           char* pv = Vl + col * VROW + i0 * 2;
;           const uint2 w = *(const uint2*)pv;
;           const float t0 = acc[nt][mi][4 * rg + 0] + bflo(w.x) * fbias;
;           const float t1 = acc[nt][mi][4 * rg + 1] + bfhi(w.x) * fbias;
;           const float t2 = acc[nt][mi][4 * rg + 2] + bflo(w.y) * fbias;
;           const float t3 = acc[nt][mi][4 * rg + 3] + bfhi(w.y) * fbias;
;           *(uint2*)pv = make_uint2(pack2(t0, t1), pack2(t2, t3));
;         }
;   }
;   __syncthreads();
;   {
;     const float wx0_0 = cw[0 * 1536 + c], wx0_1 = cw[1 * 1536 + c], wx0_2 = cw[2 * 1536 + c], bx0 = cb[c];
;     for (int e0 = tid; e0 < BG * L / 8; e0 += 256 * 4) {
	v_lshlrev_b32_e32 v37, 16, v32
	v_and_b32_e32 v32, 0xffff0000, v32
	v_fmac_f32_e32 v17, v64, v32
	v_lshlrev_b32_e32 v32, 16, v33
	v_fmac_f32_e32 v16, v64, v37
	v_fmac_f32_e32 v18, v64, v32
	v_and_b32_e32 v32, 0xffff0000, v33
	v_fmac_f32_e32 v19, v64, v32
	s_nop 0
	v_cvt_pk_bf16_f32 v16, v16, v17
	s_nop 0
	v_cvt_pk_bf16_f32 v17, v18, v19
	v_lshlrev_b32_e32 v18, 16, v34
	v_fmac_f32_e32 v20, v64, v18
	v_and_b32_e32 v18, 0xffff0000, v34
	v_fmac_f32_e32 v21, v64, v18
	v_lshlrev_b32_e32 v18, 16, v35
	v_fmac_f32_e32 v22, v64, v18
	v_and_b32_e32 v18, 0xffff0000, v35
	v_fmac_f32_e32 v23, v64, v18
	s_nop 0
	v_cvt_pk_bf16_f32 v18, v20, v21
	s_nop 0
	v_cvt_pk_bf16_f32 v19, v22, v23
	ds_write2_b64 v36, v[16:17], v[18:19] offset0:80 offset1:82
	ds_read2_b64 v[16:19], v36 offset0:84 offset1:86
	s_waitcnt lgkmcnt(0)
	v_lshlrev_b32_e32 v20, 16, v16
	v_fmac_f32_e32 v24, v64, v20
	v_and_b32_e32 v16, 0xffff0000, v16
	v_lshlrev_b32_e32 v20, 16, v18
	v_and_b32_e32 v18, 0xffff0000, v18
	v_fmac_f32_e32 v25, v64, v16
	v_lshlrev_b32_e32 v16, 16, v17
	v_fmac_f32_e32 v29, v64, v18
	v_lshlrev_b32_e32 v18, 16, v19
	v_fmac_f32_e32 v26, v64, v16
	v_and_b32_e32 v16, 0xffff0000, v17
	v_fmac_f32_e32 v30, v64, v18
	v_and_b32_e32 v18, 0xffff0000, v19
	v_fmac_f32_e32 v27, v64, v16
	s_nop 0
	v_cvt_pk_bf16_f32 v16, v24, v25
	s_nop 0
	v_cvt_pk_bf16_f32 v17, v26, v27
	v_fmac_f32_e32 v28, v64, v20
	v_fmac_f32_e32 v31, v64, v18
	s_nop 0
	v_cvt_pk_bf16_f32 v18, v28, v29
	s_nop 0
	v_cvt_pk_bf16_f32 v19, v30, v31
	ds_write2_b64 v36, v[16:17], v[18:19] offset0:84 offset1:86
	ds_read2_b64 v[16:19], v36 offset0:88 offset1:90
	s_waitcnt lgkmcnt(0)
	v_lshlrev_b32_e32 v20, 16, v16
	v_and_b32_e32 v16, 0xffff0000, v16
	v_fmac_f32_e32 v1, v64, v16
	v_lshlrev_b32_e32 v16, 16, v17
	v_fmac_f32_e32 v0, v64, v20
	v_fmac_f32_e32 v2, v64, v16
	v_and_b32_e32 v16, 0xffff0000, v17
	v_fmac_f32_e32 v3, v64, v16
	s_nop 0
	v_cvt_pk_bf16_f32 v0, v0, v1
	s_nop 0
	v_cvt_pk_bf16_f32 v1, v2, v3
	v_lshlrev_b32_e32 v2, 16, v18
	v_fmac_f32_e32 v4, v64, v2
	v_and_b32_e32 v2, 0xffff0000, v18
	v_fmac_f32_e32 v5, v64, v2
	v_lshlrev_b32_e32 v2, 16, v19
	v_fmac_f32_e32 v6, v64, v2
	v_and_b32_e32 v2, 0xffff0000, v19
	v_fmac_f32_e32 v7, v64, v2
	s_nop 0
	v_cvt_pk_bf16_f32 v2, v4, v5
	s_nop 0
	v_cvt_pk_bf16_f32 v3, v6, v7
	ds_write2_b64 v36, v[0:1], v[2:3] offset0:88 offset1:90
	ds_read2_b64 v[0:3], v36 offset0:92 offset1:94
	s_waitcnt lgkmcnt(0)
	v_lshlrev_b32_e32 v4, 16, v0
	v_fmac_f32_e32 v8, v64, v4
	v_and_b32_e32 v0, 0xffff0000, v0
	v_lshlrev_b32_e32 v4, 16, v2
	v_and_b32_e32 v2, 0xffff0000, v2
	v_fmac_f32_e32 v9, v64, v0
	v_lshlrev_b32_e32 v0, 16, v1
	v_fmac_f32_e32 v13, v64, v2
	v_lshlrev_b32_e32 v2, 16, v3
	v_fmac_f32_e32 v10, v64, v0
	v_and_b32_e32 v0, 0xffff0000, v1
	v_fmac_f32_e32 v14, v64, v2
	v_and_b32_e32 v2, 0xffff0000, v3
	v_fmac_f32_e32 v11, v64, v0
	s_nop 0
	v_cvt_pk_bf16_f32 v0, v8, v9
	s_nop 0
	v_cvt_pk_bf16_f32 v1, v10, v11
	v_fmac_f32_e32 v12, v64, v4
	v_fmac_f32_e32 v15, v64, v2
	s_nop 0
	v_cvt_pk_bf16_f32 v2, v12, v13
	s_nop 0
	v_cvt_pk_bf16_f32 v3, v14, v15
	ds_write2_b64 v36, v[0:1], v[2:3] offset0:92 offset1:94
	s_waitcnt lgkmcnt(0)
	s_barrier
	global_load_dword v38, v165, s[20:21]
	global_load_dword v39, v210, s[20:21] offset:2048
	global_load_dword v40, v209, s[20:21]
	global_load_dword v41, v165, s[22:23]
	v_lshlrev_b32_e32 v0, 4, v147
	v_and_b32_e32 v0, 0x70, v0
	v_mov_b32_e32 v147, v165
	v_add_u32_e32 v42, s15, v0
	v_or_b32_e32 v0, 0x100, v148
	v_lshl_add_u64 v[28:29], v[146:147], 1, s[74:75]
	v_lshrrev_b32_e32 v0, 1, v0
	v_lshl_add_u64 v[30:31], v[28:29], 0, s[4:5]
	s_movk_i32 s4, 0xff
	v_and_b32_e32 v44, 0xfc, v0
	v_lshrrev_b32_e32 v0, 1, v148
	v_cmp_ne_u32_e64 s[36:37], s4, v148
	s_add_i32 s4, s35, 1
	v_and_b32_e32 v47, 0x7c, v0
	v_or_b32_e32 v45, 1, v44
	v_mov_b32_e32 v46, s4
	v_or_b32_e32 v48, 1, v47
	s_mov_b64 s[4:5], 0
	s_branch .LBB0_796
